# attention ALiBi bias init with packed f32 adds; accumulator zero-init with 64-bit moves
# baseline (speedup 1.0000x reference)
.LBB0_561:
	v_mov_b32_e32 v5, v0
	v_mov_b32_e32 v3, v115
	v_readfirstlane_b32 s11, v5
	s_ashr_i32 s33, s11, 6
	s_lshl_b32 s9, s33, 5
	s_add_i32 s0, s9, s10
	s_ashr_i32 s1, s0, 31
	s_lshl_b64 s[74:75], s[0:1], 11
	s_lshl_b64 s[4:5], s[0:1], 12
	s_add_u32 s1, s68, s4
	s_addc_u32 s4, s69, s5
	s_lshl_b32 s91, s6, 7
	s_lshl_b32 s5, s6, 8
	s_add_u32 s1, s1, s5
	s_addc_u32 s5, s4, 0
	s_lshl_b32 s4, s86, 7
	v_and_b32_e32 v130, 31, v5
	s_add_u32 s4, s1, s4
	v_bfe_u32 v8, v5, 5, 1
	s_addc_u32 s5, s5, 0
	v_lshlrev_b32_e32 v2, 12, v130
	v_lshl_add_u64 v[6:7], s[4:5], 0, v[2:3]
	v_lshlrev_b32_e32 v2, 4, v8
	v_lshl_add_u64 v[6:7], v[6:7], 0, v[2:3]
	global_load_dwordx4 v[98:101], v[6:7], off
	global_load_dwordx4 v[102:105], v[6:7], off offset:32
	global_load_dwordx4 v[106:109], v[6:7], off offset:64
	global_load_dwordx4 v[110:113], v[6:7], off offset:96
	v_mul_f32_e32 v3, 0x4f800000, v4
	v_cmp_gt_f32_e32 vcc, s18, v4
	v_lshlrev_b32_e32 v10, 2, v8
	v_lshlrev_b32_e32 v131, 10, v8
	v_cndmask_b32_e32 v3, v4, v3, vcc
	v_sqrt_f32_e32 v4, v3
	v_lshlrev_b32_e32 v8, 4, v130
	v_add3_u32 v132, 0, v131, v8
	s_waitcnt vmcnt(0)
	v_add_u32_e32 v8, -1, v4
	v_add_u32_e32 v11, 1, v4
	v_fma_f32 v12, -v8, v4, v3
	v_fma_f32 v13, -v11, v4, v3
	v_cmp_ge_f32_e64 s[4:5], 0, v12
	s_mov_b32 s7, s85
	s_or_b32 s84, s84, s86
	v_cndmask_b32_e64 v4, v4, v8, s[4:5]
	v_cmp_lt_f32_e64 s[4:5], 0, v13
	s_lshl_b32 s12, s33, 9
	s_and_b32 s14, s11, 0x3fffffc0
	v_cndmask_b32_e64 v4, v4, v11, s[4:5]
	v_mul_f32_e32 v8, 0x37800000, v4
	v_cndmask_b32_e32 v4, v4, v8, vcc
	v_cmp_class_f32_e32 vcc, v3, v124
	s_lshl_b64 s[6:7], s[6:7], 22
	s_lshl_b64 s[4:5], s[84:85], 21
	v_cndmask_b32_e32 v3, v4, v3, vcc
	s_ashr_i32 s13, s12, 31
	v_readlane_b32 s16, v244, 9
	v_readlane_b32 s17, v244, 10
	s_add_u32 s1, s16, s6
	s_addc_u32 s11, s17, s7
	s_lshl_b64 s[6:7], s[12:13], 1
	s_add_u32 s12, s1, s6
	s_addc_u32 s13, s11, s7
	s_lshl_b32 s15, s33, 10
	s_addk_i32 s10, 0x100
	s_add_i32 s76, s15, s90
	s_lshr_b32 s1, s10, 6
	v_and_b32_e32 v6, 63, v5
	v_bfe_u32 v116, v5, 4, 2
	v_lshlrev_b32_e32 v7, 1, v5
	v_lshlrev_b32_e32 v9, 3, v5
	v_and_b32_e32 v129, 15, v5
	v_bfe_u32 v5, v5, 2, 2
	s_add_u32 s4, s62, s4
	v_or_b32_e32 v5, v10, v5
	s_addc_u32 s5, s63, s5
	s_add_u32 s4, s4, s6
	v_lshlrev_b32_e32 v114, 4, v6
	s_addc_u32 s5, s5, s7
	v_lshl_add_u64 v[122:123], s[4:5], 0, v[114:115]
	s_add_i32 s84, s1, -4
	s_add_i32 s77, s15, 0
	s_lshl_b32 s6, s14, 2
	v_lshl_add_u64 v[118:119], s[12:13], 0, v[114:115]
	s_mov_b64 s[10:11], 0x2000
	s_add_i32 s6, s6, 0
	v_lshl_add_u64 v[120:121], v[118:119], 0, s[10:11]
	s_add_i32 s10, s6, 0x12000
	s_add_i32 s88, s77, 0x8000
	v_and_b32_e32 v9, 24, v9
	v_add_u32_e32 v114, s10, v2
	s_mov_b64 s[94:95], s[68:69]
	s_sub_i32 s89, s1, s8
	s_mov_b64 s[96:97], s[62:63]
	s_waitcnt vmcnt(3)
	s_nop 0
	v_and_b32_e32 v8, 0xffff0000, v98
	v_lshlrev_b32_e32 v4, 16, v98
	v_mul_f32_e32 v8, v8, v8
	v_lshlrev_b32_e32 v11, 16, v99
	v_fmac_f32_e32 v8, v4, v4
	v_and_b32_e32 v12, 0xffff0000, v99
	v_fmac_f32_e32 v8, v11, v11
	v_lshlrev_b32_e32 v13, 16, v100
	v_fmac_f32_e32 v8, v12, v12
	v_and_b32_e32 v14, 0xffff0000, v100
	v_fmac_f32_e32 v8, v13, v13
	v_lshlrev_b32_e32 v15, 16, v101
	v_fmac_f32_e32 v8, v14, v14
	v_and_b32_e32 v16, 0xffff0000, v101
	v_fmac_f32_e32 v8, v15, v15
	s_waitcnt vmcnt(2)
	v_fmac_f32_e32 v8, v16, v16
	v_lshlrev_b32_e32 v4, 16, v102
	v_fmac_f32_e32 v8, v4, v4
	v_and_b32_e32 v4, 0xffff0000, v102
	v_fmac_f32_e32 v8, v4, v4
	v_lshlrev_b32_e32 v4, 16, v103
	v_fmac_f32_e32 v8, v4, v4
	v_and_b32_e32 v4, 0xffff0000, v103
	v_fmac_f32_e32 v8, v4, v4
	v_lshlrev_b32_e32 v4, 16, v104
	v_fmac_f32_e32 v8, v4, v4
	v_and_b32_e32 v4, 0xffff0000, v104
	v_fmac_f32_e32 v8, v4, v4
	v_lshlrev_b32_e32 v4, 16, v105
	v_fmac_f32_e32 v8, v4, v4
	v_and_b32_e32 v4, 0xffff0000, v105
	s_waitcnt vmcnt(1)
	v_fmac_f32_e32 v8, v4, v4
	v_lshlrev_b32_e32 v4, 16, v106
	v_fmac_f32_e32 v8, v4, v4
	v_and_b32_e32 v4, 0xffff0000, v106
	v_fmac_f32_e32 v8, v4, v4
	v_lshlrev_b32_e32 v4, 16, v107
	v_fmac_f32_e32 v8, v4, v4
	v_and_b32_e32 v4, 0xffff0000, v107
	v_fmac_f32_e32 v8, v4, v4
	v_lshlrev_b32_e32 v4, 16, v108
	v_fmac_f32_e32 v8, v4, v4
	v_and_b32_e32 v4, 0xffff0000, v108
	v_fmac_f32_e32 v8, v4, v4
	v_lshlrev_b32_e32 v4, 16, v109
	v_fmac_f32_e32 v8, v4, v4
	v_and_b32_e32 v4, 0xffff0000, v109
	s_waitcnt vmcnt(0)
	v_fmac_f32_e32 v8, v4, v4
	v_lshlrev_b32_e32 v4, 16, v110
	v_fmac_f32_e32 v8, v4, v4
	v_and_b32_e32 v4, 0xffff0000, v110
	v_fmac_f32_e32 v8, v4, v4
	v_lshlrev_b32_e32 v4, 16, v111
	v_fmac_f32_e32 v8, v4, v4
	v_and_b32_e32 v4, 0xffff0000, v111
	v_fmac_f32_e32 v8, v4, v4
	v_lshlrev_b32_e32 v4, 16, v112
	v_fmac_f32_e32 v8, v4, v4
	v_and_b32_e32 v4, 0xffff0000, v112
	v_fmac_f32_e32 v8, v4, v4
	v_lshlrev_b32_e32 v4, 16, v113
	v_fmac_f32_e32 v8, v4, v4
	v_and_b32_e32 v4, 0xffff0000, v113
	v_fmac_f32_e32 v8, v4, v4
	v_mov_b32_e32 v4, v8
	s_nop 1
	v_permlane32_swap_b32_e32 v8, v4
	v_add_f32_e32 v4, v8, v4
	v_mul_f32_e32 v8, 0x4f800000, v4
	v_cmp_gt_f32_e32 vcc, s18, v4
	v_lshlrev_b32_e32 v11, 6, v5
	v_and_or_b32 v2, v7, 32, v11
	v_cndmask_b32_e32 v4, v4, v8, vcc
	v_sqrt_f32_e32 v8, v4
	v_add3_u32 v152, v9, s90, v2
	v_or_b32_e32 v2, s9, v130
	v_sub_u32_e32 v153, 0xbf, v2
	v_add_u32_e32 v5, -1, v8
	v_fma_f32 v12, -v5, v8, v4
	v_cmp_ge_f32_e64 s[4:5], 0, v12
	v_add_u32_e32 v12, 1, v8
	v_mov_b32_e32 v2, 0
	v_cndmask_b32_e64 v5, v8, v5, s[4:5]
	v_fma_f32 v8, -v12, v8, v4
	v_cmp_lt_f32_e64 s[4:5], 0, v8
	v_mov_b32_e32 v16, v2
	v_mov_b32_e32 v17, v2
	v_cndmask_b32_e64 v5, v5, v12, s[4:5]
	v_mul_f32_e32 v8, 0x37800000, v5
	v_cndmask_b32_e32 v5, v5, v8, vcc
	v_cmp_class_f32_e32 vcc, v4, v124
	s_lshl_b64 s[4:5], s[84:85], 13
	v_mov_b32_e32 v7, v2
	v_cndmask_b32_e32 v4, v5, v4, vcc
	v_mul_f32_e32 v3, v3, v4
	v_lshl_add_u64 v[4:5], v[122:123], 0, s[4:5]
	s_mov_b32 s4, m0
	s_mov_b32 m0, s77
	s_nop 0
	global_load_lds_dwordx4 v[4:5], off
	s_mov_b32 m0, s4
	s_lshl_b64 s[4:5], s[84:85], 14
	v_lshl_add_u64 v[4:5], v[118:119], 0, s[4:5]
	s_mov_b32 s6, m0
	s_mov_b32 m0, s76
	s_nop 0
	global_load_lds_dwordx4 v[4:5], off
	s_mov_b32 m0, s6
	v_lshl_add_u64 v[4:5], v[120:121], 0, s[4:5]
	s_mov_b32 s4, m0
	s_mov_b32 m0, s88
	s_nop 0
	global_load_lds_dwordx4 v[4:5], off
	s_mov_b32 m0, s4
	s_add_i32 s4, s1, -3
	s_mov_b32 s5, s85
	s_lshl_b64 s[6:7], s[4:5], 13
	v_lshl_add_u64 v[4:5], v[122:123], 0, s[6:7]
	s_add_i32 s6, s77, 0x2000
	s_mov_b32 s7, m0
	s_mov_b32 m0, s6
	s_nop 0
	global_load_lds_dwordx4 v[4:5], off
	s_mov_b32 m0, s7
	s_lshl_b64 s[4:5], s[4:5], 14
	v_lshl_add_u64 v[4:5], v[118:119], 0, s[4:5]
	s_add_i32 s6, s77, 0xa000
	s_mov_b32 s7, m0
	s_mov_b32 m0, s6
	s_nop 0
	global_load_lds_dwordx4 v[4:5], off
	s_mov_b32 m0, s7
	v_lshl_add_u64 v[4:5], v[120:121], 0, s[4:5]
	s_add_i32 s4, s77, 0xc000
	s_mov_b32 s5, m0
	s_mov_b32 m0, s4
	s_nop 0
	global_load_lds_dwordx4 v[4:5], off
	s_mov_b32 m0, s5
	v_fmamk_f32 v150, v3, 0x3f8020c5, v125
	v_or_b32_e32 v3, s0, v130
	s_lshl_b32 s0, s33, 2
	s_add_i32 s68, s0, 0
	v_sub_u32_e32 v151, v10, v3
	v_cmp_gt_u32_e64 s[4:5], 32, v6
	v_cmp_eq_u32_e64 s[6:7], 0, v6
	v_mov_b32_e32 v3, v2
	v_mov_b32_e32 v4, v2
	v_mov_b32_e32 v5, v2
	v_mov_b32_e32 v6, v2
	v_mov_b32_e32 v8, v2
	v_mov_b32_e32 v9, v2
	v_mov_b32_e32 v10, v2
	v_mov_b32_e32 v11, v2
	v_mov_b32_e32 v12, v2
	v_mov_b32_e32 v13, v2
	v_mov_b32_e32 v14, v2
	v_mov_b32_e32 v15, v2
	v_mov_b64_e32 v[64:65], v[16:17]
	v_mov_b64_e32 v[48:49], v[16:17]
	v_mov_b64_e32 v[32:33], v[16:17]
	v_mul_f32_e32 v133, 0, v117
	v_add_f32_e32 v134, v117, v117
	v_mul_f32_e32 v135, 0x40400000, v117
	v_mul_f32_e32 v136, 0x41000000, v117
	v_mul_f32_e32 v137, 0x41100000, v117
	v_mul_f32_e32 v138, 0x41200000, v117
	v_mul_f32_e32 v139, 0x41300000, v117
	v_mul_f32_e32 v140, 0x41800000, v117
	v_mul_f32_e32 v141, 0x41880000, v117
	v_mul_f32_e32 v142, 0x41900000, v117
	v_mul_f32_e32 v143, 0x41980000, v117
	v_mul_f32_e32 v144, 0x41c00000, v117
	v_mul_f32_e32 v145, 0x41c80000, v117
	v_mul_f32_e32 v146, 0x41d00000, v117
	v_mul_f32_e32 v148, 0x41d80000, v117
	v_mul_f32_e32 v149, 0x42000000, v117
	v_mov_b32_e32 v190, v133
	v_mov_b32_e32 v191, v117
	v_mov_b32_e32 v216, v146
	v_mov_b32_e32 v217, v148
	s_add_i32 s68, s68, 0x22800
	v_lshl_add_u32 v147, v130, 2, s10
	s_max_i32 s69, s89, 0
	s_mov_b32 s80, 0
	v_mov_b64_e32 v[62:63], v[14:15]
	v_mov_b64_e32 v[60:61], v[12:13]
	v_mov_b64_e32 v[58:59], v[10:11]
	v_mov_b64_e32 v[56:57], v[8:9]
	v_mov_b64_e32 v[54:55], v[6:7]
	v_mov_b64_e32 v[52:53], v[4:5]
	v_mov_b64_e32 v[50:51], v[2:3]
	v_mov_b64_e32 v[46:47], v[14:15]
	v_mov_b64_e32 v[44:45], v[12:13]
	v_mov_b64_e32 v[42:43], v[10:11]
	v_mov_b64_e32 v[40:41], v[8:9]
	v_mov_b64_e32 v[38:39], v[6:7]
	v_mov_b64_e32 v[36:37], v[4:5]
	v_mov_b64_e32 v[34:35], v[2:3]
	v_mov_b64_e32 v[30:31], v[14:15]
	v_mov_b64_e32 v[28:29], v[12:13]
	v_mov_b64_e32 v[26:27], v[10:11]
	v_mov_b64_e32 v[24:25], v[8:9]
	v_mov_b64_e32 v[22:23], v[6:7]
	v_mov_b64_e32 v[20:21], v[4:5]
	v_mov_b64_e32 v[18:19], v[2:3]
	s_mov_b32 s83, 0
	s_mov_b32 s81, 0
	v_mov_b32_e32 v154, v2
	v_mov_b32_e32 v155, v2
	s_cmp_eq_u32 s69, s83
	s_cbranch_scc0 .LBB0_563

.LBB0_572:
	s_add_i32 s9, s9, 3
	s_waitcnt lgkmcnt(0)
	v_lshl_add_u32 v157, s81, 13, v132
	s_cmp_lt_u32 s83, 4
	ds_read_b128 v[192:195], v157
	ds_read_b128 v[200:203], v157 offset:2048
	ds_read_b128 v[208:211], v157 offset:4096
	ds_read_b128 v[220:223], v157 offset:6144
	ds_read_b128 v[196:199], v157 offset:512
	ds_read_b128 v[204:207], v157 offset:2560
	ds_read_b128 v[212:215], v157 offset:4608
	ds_read_b128 v[228:231], v157 offset:6656
	s_cselect_b32 s8, s8, s9
	v_lshl_add_u32 v156, s8, 6, v151
	v_cvt_f32_i32_e32 v66, v156
	s_cmp_lt_i32 s8, s84
	v_fma_f32 v81, v117, v66, -v155
	v_add_f32_e32 v97, v149, v81
	v_pk_add_f32 v[66:67], v[190:191], v[80:81] op_sel:[0,1] op_sel_hi:[1,1]
	v_pk_add_f32 v[68:69], v[134:135], v[80:81] op_sel:[0,1] op_sel_hi:[1,1]
	v_pk_add_f32 v[70:71], v[136:137], v[80:81] op_sel:[0,1] op_sel_hi:[1,1]
	v_pk_add_f32 v[72:73], v[138:139], v[80:81] op_sel:[0,1] op_sel_hi:[1,1]
	v_pk_add_f32 v[74:75], v[140:141], v[80:81] op_sel:[0,1] op_sel_hi:[1,1]
	v_pk_add_f32 v[76:77], v[142:143], v[80:81] op_sel:[0,1] op_sel_hi:[1,1]
	v_pk_add_f32 v[78:79], v[144:145], v[80:81] op_sel:[0,1] op_sel_hi:[1,1]
	v_pk_add_f32 v[80:81], v[216:217], v[80:81] op_sel:[0,1] op_sel_hi:[1,1]
	v_pk_add_f32 v[82:83], v[190:191], v[96:97] op_sel:[0,1] op_sel_hi:[1,1]
	v_pk_add_f32 v[84:85], v[134:135], v[96:97] op_sel:[0,1] op_sel_hi:[1,1]
	v_pk_add_f32 v[86:87], v[136:137], v[96:97] op_sel:[0,1] op_sel_hi:[1,1]
	v_pk_add_f32 v[88:89], v[138:139], v[96:97] op_sel:[0,1] op_sel_hi:[1,1]
	v_pk_add_f32 v[90:91], v[140:141], v[96:97] op_sel:[0,1] op_sel_hi:[1,1]
	v_pk_add_f32 v[92:93], v[142:143], v[96:97] op_sel:[0,1] op_sel_hi:[1,1]
	v_pk_add_f32 v[94:95], v[144:145], v[96:97] op_sel:[0,1] op_sel_hi:[1,1]
	v_pk_add_f32 v[96:97], v[216:217], v[96:97] op_sel:[0,1] op_sel_hi:[1,1]
	s_waitcnt lgkmcnt(4)
	v_mfma_f32_32x32x16_bf16 v[66:81], v[192:195], v[98:101], v[66:81]
	v_mfma_f32_32x32x16_bf16 v[66:81], v[200:203], v[102:105], v[66:81]
	v_mfma_f32_32x32x16_bf16 v[66:81], v[208:211], v[106:109], v[66:81]
	v_mfma_f32_32x32x16_bf16 v[66:81], v[220:223], v[110:113], v[66:81]
	s_waitcnt lgkmcnt(0)
	s_nop 1
	v_mfma_f32_32x32x16_bf16 v[82:97], v[196:199], v[98:101], v[82:97]
	v_mfma_f32_32x32x16_bf16 v[82:97], v[204:207], v[102:105], v[82:97]
	v_mfma_f32_32x32x16_bf16 v[82:97], v[212:215], v[106:109], v[82:97]
	v_mfma_f32_32x32x16_bf16 v[82:97], v[228:231], v[110:113], v[82:97]
	s_cbranch_scc1 .LBB0_574
	s_movk_i32 s36, 0xffe6
	s_movk_i32 s64, 0xffe5
	s_movk_i32 s34, 0xffe7
	v_cmp_lt_i32_e64 s[62:63], s36, v156
	v_cmp_lt_i32_e64 s[64:65], s64, v156
	s_movk_i32 s30, 0xffe8
	v_cmp_lt_i32_e64 s[60:61], s34, v156
	s_and_b64 s[62:63], s[64:65], s[62:63]
	s_movk_i32 s28, 0xffed
	v_cmp_lt_i32_e64 s[58:59], s30, v156
	s_and_b64 s[60:61], s[62:63], s[60:61]
	s_movk_i32 s26, 0xffee
	v_cmp_lt_i32_e64 s[56:57], s28, v156
	s_and_b64 s[58:59], s[60:61], s[58:59]
	s_movk_i32 s24, 0xffef
	v_cmp_lt_i32_e64 s[54:55], s26, v156
	s_and_b64 s[56:57], s[58:59], s[56:57]
	v_cmp_lt_i32_e64 s[52:53], s24, v156
	s_and_b64 s[54:55], s[56:57], s[54:55]
	v_cmp_lt_i32_e64 s[50:51], -16, v156
	s_and_b64 s[52:53], s[54:55], s[52:53]
	v_cmp_lt_i32_e64 s[48:49], -11, v156
	s_and_b64 s[50:51], s[52:53], s[50:51]
	v_cmp_lt_i32_e64 s[46:47], -10, v156
	s_and_b64 s[48:49], s[50:51], s[48:49]
	v_cmp_lt_i32_e64 s[44:45], -9, v156
	s_and_b64 s[46:47], s[48:49], s[46:47]
	s_movk_i32 s10, 0xffe0
	v_cmp_lt_i32_e64 s[42:43], -8, v156
	s_and_b64 s[44:45], s[46:47], s[44:45]
	v_cmp_gt_i32_e64 s[8:9], 1, v156
	v_cmp_lt_i32_e32 vcc, s10, v156
	v_cmp_gt_i32_e64 s[10:11], 0, v156
	v_cmp_lt_i32_e64 s[40:41], -3, v156
	s_and_b64 s[42:43], s[44:45], s[42:43]
	s_or_b64 s[8:9], s[10:11], s[8:9]
	v_cmp_lt_i32_e64 s[38:39], -2, v156
	s_and_b64 s[40:41], s[42:43], s[40:41]
	v_cndmask_b32_e64 v157, v127, v67, s[10:11]
	v_cndmask_b32_e64 v158, v127, v66, s[8:9]
	s_and_b64 s[38:39], s[40:41], s[38:39]
	s_movk_i32 s36, 0xffc6
	v_cndmask_b32_e64 v66, v66, v158, s[38:39]
	v_cndmask_b32_e64 v68, v68, v127, s[38:39]
	v_cndmask_b32_e64 v67, v67, v157, s[38:39]
	s_movk_i32 s38, 0xffc5
	s_movk_i32 s34, 0xffc7
	v_cmp_lt_i32_e64 s[36:37], s36, v156
	v_cmp_lt_i32_e64 s[38:39], s38, v156
	s_movk_i32 s30, 0xffc8
	v_cmp_lt_i32_e64 s[34:35], s34, v156
	s_and_b64 s[36:37], s[38:39], s[36:37]
	s_movk_i32 s28, 0xffcd
	v_cmp_lt_i32_e64 s[30:31], s30, v156
	s_and_b64 s[34:35], s[36:37], s[34:35]
	s_movk_i32 s26, 0xffce
	v_cmp_lt_i32_e64 s[28:29], s28, v156
	s_and_b64 s[30:31], s[34:35], s[30:31]
	s_movk_i32 s24, 0xffcf
	v_cmp_lt_i32_e64 s[26:27], s26, v156
	s_and_b64 s[28:29], s[30:31], s[28:29]
	s_movk_i32 s22, 0xffd0
	v_cmp_lt_i32_e64 s[24:25], s24, v156
	s_and_b64 s[26:27], s[28:29], s[26:27]
	s_movk_i32 s20, 0xffd5
	v_cmp_lt_i32_e64 s[22:23], s22, v156
	s_and_b64 s[24:25], s[26:27], s[24:25]
	s_movk_i32 s18, 0xffd6
	v_cmp_lt_i32_e64 s[20:21], s20, v156
	s_and_b64 s[22:23], s[24:25], s[22:23]
	s_movk_i32 s16, 0xffd7
	v_cmp_lt_i32_e64 s[18:19], s18, v156
	s_and_b64 s[20:21], s[22:23], s[20:21]
	s_movk_i32 s14, 0xffd8
	v_cmp_lt_i32_e64 s[16:17], s16, v156
	s_and_b64 s[18:19], s[20:21], s[18:19]
	s_movk_i32 s12, 0xffdd
	v_cmp_lt_i32_e64 s[14:15], s14, v156
	s_and_b64 s[16:17], s[18:19], s[16:17]
	s_movk_i32 s10, 0xffde
	v_cmp_lt_i32_e64 s[12:13], s12, v156
	s_and_b64 s[14:15], s[16:17], s[14:15]
	s_movk_i32 s8, 0xffdf
	v_cmp_lt_i32_e64 s[10:11], s10, v156
	s_and_b64 s[12:13], s[14:15], s[12:13]
	v_cmp_lt_i32_e64 s[8:9], s8, v156
	s_and_b64 s[10:11], s[12:13], s[10:11]
	s_and_b64 s[8:9], s[10:11], s[8:9]
	s_and_b64 vcc, s[8:9], vcc
	v_cndmask_b32_e64 v81, v81, v127, s[64:65]
	v_cndmask_b32_e64 v80, v80, v127, s[62:63]
	v_cndmask_b32_e64 v79, v79, v127, s[60:61]
	v_cndmask_b32_e64 v78, v78, v127, s[58:59]
	v_cndmask_b32_e64 v77, v77, v127, s[56:57]
	v_cndmask_b32_e64 v76, v76, v127, s[54:55]
	v_cndmask_b32_e64 v75, v75, v127, s[52:53]
	v_cndmask_b32_e64 v74, v74, v127, s[50:51]
	v_cndmask_b32_e64 v73, v73, v127, s[48:49]
	v_cndmask_b32_e64 v72, v72, v127, s[46:47]
	v_cndmask_b32_e64 v71, v71, v127, s[44:45]
	v_cndmask_b32_e64 v70, v70, v127, s[42:43]
	v_cndmask_b32_e64 v69, v69, v127, s[40:41]
	v_cndmask_b32_e64 v97, v97, v127, s[38:39]
	v_cndmask_b32_e64 v96, v96, v127, s[36:37]
	v_cndmask_b32_e64 v95, v95, v127, s[34:35]
	v_cndmask_b32_e64 v94, v94, v127, s[30:31]
	v_cndmask_b32_e64 v93, v93, v127, s[28:29]
	v_cndmask_b32_e64 v92, v92, v127, s[26:27]
	v_cndmask_b32_e64 v91, v91, v127, s[24:25]
	v_cndmask_b32_e64 v90, v90, v127, s[22:23]
	v_cndmask_b32_e64 v89, v89, v127, s[20:21]
	v_cndmask_b32_e64 v88, v88, v127, s[18:19]
	v_cndmask_b32_e64 v87, v87, v127, s[16:17]
	v_cndmask_b32_e64 v86, v86, v127, s[14:15]
	v_cndmask_b32_e64 v85, v85, v127, s[12:13]
	v_cndmask_b32_e64 v84, v84, v127, s[10:11]
	v_cndmask_b32_e64 v83, v83, v127, s[8:9]
	v_cndmask_b32_e32 v82, v82, v127, vcc
